# FoX loop: the current tile id is read from the LDS tile list at the top of each body (one LDS round trip per tile removed)
# speedup vs baseline: 1.0087x; 1.0001x over previous
.LBB0_794:
	v_mov_b32_e32 v208, s19
	ds_read_b32 v208, v208
	s_mul_i32 s8, s17, 0x4900
	s_add_i32 s20, s33, s8
	v_add_u32_e32 v0, s20, v173
	v_add_u32_e32 v0, v0, v156
	ds_read_b128 v[52:55], v0
	ds_read_b128 v[88:91], v0 offset:32
	ds_read_b128 v[92:95], v0 offset:4608
	ds_read_b128 v[96:99], v0 offset:4640
	ds_read_b128 v[100:103], v0 offset:64
	ds_read_b128 v[104:107], v0 offset:96
	ds_read_b128 v[108:111], v0 offset:4672
	ds_read_b128 v[112:115], v0 offset:4704
	s_waitcnt lgkmcnt(7)
	v_mfma_f32_32x32x16_bf16 v[68:83], v[52:55], v[116:119], v[4:19]
	s_waitcnt lgkmcnt(5)
	v_mfma_f32_32x32x16_bf16 v[52:67], v[92:95], v[116:119], v[4:19]
	v_mfma_f32_32x32x16_bf16 v[68:83], v[88:91], v[120:123], v[68:83]
	ds_read_b128 v[88:91], v0 offset:128
	ds_read_b128 v[92:95], v0 offset:4736
	s_waitcnt lgkmcnt(6)
	v_mfma_f32_32x32x16_bf16 v[52:67], v[96:99], v[120:123], v[52:67]
	s_waitcnt lgkmcnt(5)
	v_mfma_f32_32x32x16_bf16 v[68:83], v[100:103], v[124:127], v[68:83]
	s_waitcnt lgkmcnt(3)
	v_mfma_f32_32x32x16_bf16 v[52:67], v[108:111], v[124:127], v[52:67]
	v_mfma_f32_32x32x16_bf16 v[68:83], v[104:107], v[128:131], v[68:83]
	s_waitcnt lgkmcnt(2)
	v_mfma_f32_32x32x16_bf16 v[52:67], v[112:115], v[128:131], v[52:67]
	s_waitcnt lgkmcnt(1)
	v_mfma_f32_32x32x16_bf16 v[68:83], v[88:91], v[148:151], v[68:83]
	s_waitcnt lgkmcnt(0)
	v_mfma_f32_32x32x16_bf16 v[52:67], v[92:95], v[148:151], v[52:67]
	v_mov_b32_e32 v2, v208
	v_cmp_gt_i32_e32 vcc, s18, v2
	s_cbranch_vccnz .LBB0_796
	v_readfirstlane_b32 s34, v2
	v_readfirstlane_b32 s35, v154
	s_nop 1
	s_lshl_b32 s34, s34, 1
	s_lshr_b32 s35, s35, 5
	s_cmp_lt_u32 s34, s35
	s_cbranch_scc1 .Lfm1_d0
	s_cmp_eq_u32 s34, s35
	s_cbranch_scc1 .Lfm1_t0
	v_mov_b32_e32 v68, v185
	v_mov_b32_e32 v69, v185
	v_mov_b32_e32 v70, v185
	v_mov_b32_e32 v71, v185
	v_mov_b32_e32 v72, v185
	v_mov_b32_e32 v73, v185
	v_mov_b32_e32 v74, v185
	v_mov_b32_e32 v75, v185
	v_mov_b32_e32 v76, v185
	v_mov_b32_e32 v77, v185
	v_mov_b32_e32 v78, v185
	v_mov_b32_e32 v79, v185
	v_mov_b32_e32 v80, v185
	v_mov_b32_e32 v81, v185
	v_mov_b32_e32 v82, v185
	v_mov_b32_e32 v83, v185
	s_branch .Lfm1_d0

.LBB0_807:
	v_mov_b32_e32 v208, s19
	ds_read_b32 v208, v208 offset:4
	s_mulk_i32 s22, 0x4900
	v_add_u32_e32 v0, s22, v174
	ds_read_b128 v[52:55], v0
	ds_read_b128 v[56:59], v0 offset:32
	ds_read_b128 v[60:63], v0 offset:4608
	ds_read_b128 v[64:67], v0 offset:4640
	ds_read_b128 v[68:71], v0 offset:64
	ds_read_b128 v[72:75], v0 offset:96
	ds_read_b128 v[76:79], v0 offset:4672
	ds_read_b128 v[80:83], v0 offset:4704
	s_waitcnt lgkmcnt(7)
	v_mfma_f32_32x32x16_bf16 v[100:115], v[52:55], v[116:119], v[4:19]
	s_waitcnt lgkmcnt(5)
	v_mfma_f32_32x32x16_bf16 v[84:99], v[60:63], v[116:119], v[4:19]
	v_mfma_f32_32x32x16_bf16 v[100:115], v[56:59], v[120:123], v[100:115]
	ds_read_b128 v[52:55], v0 offset:128
	ds_read_b128 v[56:59], v0 offset:4736
	s_waitcnt lgkmcnt(6)
	v_mfma_f32_32x32x16_bf16 v[84:99], v[64:67], v[120:123], v[84:99]
	s_waitcnt lgkmcnt(5)
	v_mfma_f32_32x32x16_bf16 v[100:115], v[68:71], v[124:127], v[100:115]
	s_waitcnt lgkmcnt(3)
	v_mfma_f32_32x32x16_bf16 v[84:99], v[76:79], v[124:127], v[84:99]
	v_mfma_f32_32x32x16_bf16 v[100:115], v[72:75], v[128:131], v[100:115]
	s_waitcnt lgkmcnt(2)
	v_mfma_f32_32x32x16_bf16 v[84:99], v[80:83], v[128:131], v[84:99]
	s_waitcnt lgkmcnt(1)
	v_mfma_f32_32x32x16_bf16 v[100:115], v[52:55], v[148:151], v[100:115]
	s_waitcnt lgkmcnt(0)
	v_mfma_f32_32x32x16_bf16 v[84:99], v[56:59], v[148:151], v[84:99]
	v_mov_b32_e32 v2, v208
	v_cmp_gt_i32_e32 vcc, s18, v2
	s_cbranch_vccnz .LBB0_809
	v_readfirstlane_b32 s34, v2
	v_readfirstlane_b32 s35, v154
	s_nop 1
	s_lshl_b32 s34, s34, 1
	s_lshr_b32 s35, s35, 5
	s_cmp_lt_u32 s34, s35
	s_cbranch_scc1 .Lfm2_d0
	s_cmp_eq_u32 s34, s35
	s_cbranch_scc1 .Lfm2_t0
	v_mov_b32_e32 v100, v185
	v_mov_b32_e32 v101, v185
	v_mov_b32_e32 v102, v185
	v_mov_b32_e32 v103, v185
	v_mov_b32_e32 v104, v185
	v_mov_b32_e32 v105, v185
	v_mov_b32_e32 v106, v185
	v_mov_b32_e32 v107, v185
	v_mov_b32_e32 v108, v185
	v_mov_b32_e32 v109, v185
	v_mov_b32_e32 v110, v185
	v_mov_b32_e32 v111, v185
	v_mov_b32_e32 v112, v185
	v_mov_b32_e32 v113, v185
	v_mov_b32_e32 v114, v185
	v_mov_b32_e32 v115, v185
	s_branch .Lfm2_d0
